# final rmsnorm: weight quads loaded once, a row's 8 quads + sum of squares fetched together and one row ahead (was 32 serialized round trips per wave); last-layer xb stores skipped
# speedup vs baseline: 1.0114x; 1.0008x over previous
.LBB0_1852:
	v_lshl_add_u32 v204, s67, 8, v218
	v_lshl_or_b32 v200, s66, 8, v220
	v_ashrrev_i32_e32 v201, 31, v200
	v_ashrrev_i32_e32 v205, 31, v204
	v_lshl_add_u64 v[202:203], v[200:201], 2, s[0:1]
	v_lshlrev_b64 v[114:115], 13, v[204:205]
	v_lshl_add_u64 v[248:249], v[202:203], 0, v[114:115]
	flat_load_dwordx4 v[232:235], v[248:249]
	flat_load_dwordx4 v[236:239], v[248:249] offset:16
	flat_load_dwordx4 v[240:243], v[248:249] offset:512
	flat_load_dwordx4 v[244:247], v[248:249] offset:528
	v_or_b32_e32 v214, 16, v204
	v_ashrrev_i32_e32 v215, 31, v214
	v_or_b32_e32 v210, 32, v204
	v_lshlrev_b64 v[114:115], 13, v[214:215]
	v_ashrrev_i32_e32 v211, 31, v210
	v_or_b32_e32 v206, 48, v204
	v_lshl_add_u64 v[216:217], v[202:203], 0, v[114:115]
	v_lshlrev_b64 v[114:115], 13, v[210:211]
	v_ashrrev_i32_e32 v207, 31, v206
	v_lshl_add_u64 v[212:213], v[202:203], 0, v[114:115]
	v_lshlrev_b64 v[114:115], 13, v[206:207]
	v_lshl_add_u64 v[208:209], v[202:203], 0, v[114:115]
	flat_load_dwordx4 v[174:177], v[216:217]
	flat_load_dwordx4 v[170:173], v[216:217] offset:16
	flat_load_dwordx4 v[166:169], v[216:217] offset:512
	flat_load_dwordx4 v[162:165], v[216:217] offset:528
	flat_load_dwordx4 v[158:161], v[212:213]
	flat_load_dwordx4 v[154:157], v[212:213] offset:16
	flat_load_dwordx4 v[134:137], v[212:213] offset:512
	flat_load_dwordx4 v[130:133], v[212:213] offset:528
	flat_load_dwordx4 v[142:145], v[208:209]
	flat_load_dwordx4 v[138:141], v[208:209] offset:16
	flat_load_dwordx4 v[118:121], v[208:209] offset:512
	flat_load_dwordx4 v[114:117], v[208:209] offset:528
	v_lshlrev_b64 v[250:251], 11, v[204:205]
	v_lshl_add_u64 v[250:251], v[250:251], 0, v[200:201]
	s_waitcnt vmcnt(0) lgkmcnt(0)
	v_readlane_b32 s100, v255, 10
	v_readlane_b32 s101, v255, 11
	v_pk_add_f32 v[152:153], v[152:153], v[234:235]
	v_pk_add_f32 v[150:151], v[150:151], v[232:233]
	v_pk_add_f32 v[148:149], v[148:149], v[238:239]
	v_pk_add_f32 v[146:147], v[146:147], v[236:237]
	flat_store_dwordx4 v[248:249], v[150:153]
	flat_store_dwordx4 v[248:249], v[146:149] offset:16
	v_cvt_pk_bf16_f32 v232, v150, v151
	v_cvt_pk_bf16_f32 v233, v152, v153
	v_cvt_pk_bf16_f32 v234, v146, v147
	v_lshlrev_b64 v[236:237], 1, v[250:251]
	v_mul_f32_e32 v151, v151, v151
	v_fmac_f32_e32 v151, v150, v150
	v_mul_f32_e32 v150, v153, v153
	v_fmac_f32_e32 v150, v152, v152
	v_mul_f32_e32 v147, v147, v147
	v_add_f32_e32 v150, v151, v150
	v_fmac_f32_e32 v147, v146, v146
	v_add_f32_e32 v146, v150, v147
	v_mul_f32_e32 v147, v149, v149
	v_lshl_add_u64 v[238:239], s[6:7], 0, v[236:237]
	v_fmac_f32_e32 v147, v148, v148
	v_pk_add_f32 v[128:129], v[128:129], v[242:243]
	v_pk_add_f32 v[126:127], v[126:127], v[240:241]
	v_cvt_pk_bf16_f32 v235, v148, v149
	s_mov_b64 exec, s[100:101]
	flat_store_dwordx4 v[238:239], v[232:235]
	s_mov_b64 exec, -1
	v_add_f32_e32 v152, v147, v146
	v_pk_add_f32 v[124:125], v[124:125], v[246:247]
	v_pk_add_f32 v[122:123], v[122:123], v[244:245]
	flat_store_dwordx4 v[248:249], v[126:129] offset:512
	flat_store_dwordx4 v[248:249], v[122:125] offset:528
	v_cvt_pk_bf16_f32 v146, v126, v127
	v_cvt_pk_bf16_f32 v147, v128, v129
	v_cvt_pk_bf16_f32 v148, v122, v123
	v_cvt_pk_bf16_f32 v149, v124, v125
	s_nop 0
	v_mul_f32_e32 v127, v127, v127
	v_fmac_f32_e32 v127, v126, v126
	v_mul_f32_e32 v126, v129, v129
	v_fmac_f32_e32 v126, v128, v128
	v_mul_f32_e32 v123, v123, v123
	v_add_f32_e32 v126, v127, v126
	v_fmac_f32_e32 v123, v122, v122
	v_add_f32_e32 v122, v126, v123
	v_mul_f32_e32 v123, v125, v125
	v_fmac_f32_e32 v123, v124, v124
	v_and_b32_e32 v124, 64, v226
	v_add_f32_e32 v122, v123, v122
	v_xor_b32_e32 v123, 16, v226
	v_add_u32_e32 v124, 64, v124
	v_or_b32_e32 v236, 0x100, v236
	v_cmp_lt_i32_e32 vcc, v123, v124
	v_lshl_add_u64 v[150:151], s[6:7], 0, v[236:237]
	s_mov_b64 exec, s[100:101]
	flat_store_dwordx4 v[150:151], v[146:149]
	s_mov_b64 exec, -1
	v_cndmask_b32_e32 v123, v226, v123, vcc
	v_add_f32_e32 v122, v152, v122
	v_lshlrev_b32_e32 v146, 2, v123
	ds_bpermute_b32 v123, v146, v122
	s_waitcnt lgkmcnt(0)
	v_add_f32_e32 v122, v122, v123
	v_xor_b32_e32 v123, 32, v226
	v_cmp_lt_i32_e32 vcc, v123, v124
	s_nop 1
	v_cndmask_b32_e32 v123, v226, v123, vcc
	v_lshlrev_b32_e32 v147, 2, v123
	ds_bpermute_b32 v123, v147, v122
	s_and_saveexec_b64 s[50:51], s[38:39]
	s_cbranch_execz .LBB0_1854
	v_lshl_add_u64 v[124:125], v[204:205], 2, s[44:45]
	s_waitcnt lgkmcnt(0)
	v_add_f32_e32 v122, v122, v123
	flat_atomic_add_f32 v[124:125], v122
.LBB0_1854:
	s_or_b64 exec, exec, s[50:51]
	s_waitcnt lgkmcnt(0)
	v_lshlrev_b64 v[122:123], 11, v[214:215]
	v_pk_add_f32 v[112:113], v[112:113], v[176:177]
	v_pk_add_f32 v[110:111], v[110:111], v[174:175]
	v_lshl_add_u64 v[126:127], v[122:123], 0, v[200:201]
	v_pk_add_f32 v[108:109], v[108:109], v[172:173]
	v_pk_add_f32 v[106:107], v[106:107], v[170:171]
	flat_store_dwordx4 v[216:217], v[110:113]
	flat_store_dwordx4 v[216:217], v[106:109] offset:16
	v_cvt_pk_bf16_f32 v122, v110, v111
	v_cvt_pk_bf16_f32 v123, v112, v113
	v_cvt_pk_bf16_f32 v124, v106, v107
	v_pk_add_f32 v[104:105], v[104:105], v[168:169]
	v_mul_f32_e32 v111, v111, v111
	v_fmac_f32_e32 v111, v110, v110
	v_mul_f32_e32 v110, v113, v113
	v_fmac_f32_e32 v110, v112, v112
	v_mul_f32_e32 v107, v107, v107
	v_add_f32_e32 v110, v111, v110
	v_fmac_f32_e32 v107, v106, v106
	v_add_f32_e32 v106, v110, v107
	v_mul_f32_e32 v107, v109, v109
	v_fmac_f32_e32 v107, v108, v108
	v_pk_add_f32 v[102:103], v[102:103], v[166:167]
	v_cvt_pk_bf16_f32 v125, v108, v109
	v_add_f32_e32 v106, v107, v106
	v_mul_f32_e32 v107, v103, v103
	v_mul_f32_e32 v108, v105, v105
	v_pk_add_f32 v[98:99], v[98:99], v[162:163]
	v_fmac_f32_e32 v107, v102, v102
	v_fmac_f32_e32 v108, v104, v104
	v_add_f32_e32 v107, v107, v108
	v_mul_f32_e32 v108, v99, v99
	v_pk_add_f32 v[100:101], v[100:101], v[164:165]
	v_fmac_f32_e32 v108, v98, v98
	v_add_f32_e32 v107, v107, v108
	v_mul_f32_e32 v108, v101, v101
	v_fmac_f32_e32 v108, v100, v100
	v_add_f32_e32 v107, v108, v107
	v_add_f32_e32 v106, v106, v107
	ds_bpermute_b32 v107, v146, v106
	v_lshlrev_b64 v[126:127], 1, v[126:127]
	v_lshl_add_u64 v[128:129], s[6:7], 0, v[126:127]
	s_mov_b64 exec, s[100:101]
	flat_store_dwordx4 v[128:129], v[122:125]
	s_mov_b64 exec, -1
	flat_store_dwordx4 v[216:217], v[102:105] offset:512
	flat_store_dwordx4 v[216:217], v[98:101] offset:528
	v_or_b32_e32 v126, 0x100, v126
	v_cvt_pk_bf16_f32 v102, v102, v103
	v_cvt_pk_bf16_f32 v103, v104, v105
	v_cvt_pk_bf16_f32 v104, v98, v99
	v_cvt_pk_bf16_f32 v105, v100, v101
	s_waitcnt lgkmcnt(0)
	v_add_f32_e32 v98, v106, v107
	ds_bpermute_b32 v99, v147, v98
	v_lshl_add_u64 v[100:101], s[6:7], 0, v[126:127]
	s_mov_b64 exec, s[100:101]
	flat_store_dwordx4 v[100:101], v[102:105]
	s_mov_b64 exec, -1
	s_and_saveexec_b64 s[50:51], s[38:39]
	s_cbranch_execz .LBB0_1856
	v_lshl_add_u64 v[100:101], v[214:215], 2, s[44:45]
	s_waitcnt lgkmcnt(0)
	v_add_f32_e32 v98, v98, v99
	flat_atomic_add_f32 v[100:101], v98
.LBB0_1856:
	s_or_b64 exec, exec, s[50:51]
	s_waitcnt lgkmcnt(0)
	v_lshlrev_b64 v[98:99], 11, v[210:211]
	v_pk_add_f32 v[96:97], v[96:97], v[160:161]
	v_pk_add_f32 v[94:95], v[94:95], v[158:159]
	v_lshl_add_u64 v[102:103], v[98:99], 0, v[200:201]
	v_pk_add_f32 v[92:93], v[92:93], v[156:157]
	v_pk_add_f32 v[90:91], v[90:91], v[154:155]
	flat_store_dwordx4 v[212:213], v[94:97]
	flat_store_dwordx4 v[212:213], v[90:93] offset:16
	v_cvt_pk_bf16_f32 v98, v94, v95
	v_cvt_pk_bf16_f32 v99, v96, v97
	v_cvt_pk_bf16_f32 v100, v90, v91
	v_pk_add_f32 v[88:89], v[88:89], v[136:137]
	v_mul_f32_e32 v95, v95, v95
	v_fmac_f32_e32 v95, v94, v94
	v_mul_f32_e32 v94, v97, v97
	v_fmac_f32_e32 v94, v96, v96
	v_mul_f32_e32 v91, v91, v91
	v_add_f32_e32 v94, v95, v94
	v_fmac_f32_e32 v91, v90, v90
	v_add_f32_e32 v90, v94, v91
	v_mul_f32_e32 v91, v93, v93
	v_fmac_f32_e32 v91, v92, v92
	v_pk_add_f32 v[86:87], v[86:87], v[134:135]
	v_cvt_pk_bf16_f32 v101, v92, v93
	v_add_f32_e32 v90, v91, v90
	v_mul_f32_e32 v91, v87, v87
	v_mul_f32_e32 v92, v89, v89
	v_pk_add_f32 v[82:83], v[82:83], v[130:131]
	v_fmac_f32_e32 v91, v86, v86
	v_fmac_f32_e32 v92, v88, v88
	v_add_f32_e32 v91, v91, v92
	v_mul_f32_e32 v92, v83, v83
	v_pk_add_f32 v[84:85], v[84:85], v[132:133]
	v_fmac_f32_e32 v92, v82, v82
	v_add_f32_e32 v91, v91, v92
	v_mul_f32_e32 v92, v85, v85
	v_fmac_f32_e32 v92, v84, v84
	v_add_f32_e32 v91, v92, v91
	v_add_f32_e32 v90, v90, v91
	ds_bpermute_b32 v91, v146, v90
	v_lshlrev_b64 v[102:103], 1, v[102:103]
	v_lshl_add_u64 v[104:105], s[6:7], 0, v[102:103]
	s_mov_b64 exec, s[100:101]
	flat_store_dwordx4 v[104:105], v[98:101]
	s_mov_b64 exec, -1
	flat_store_dwordx4 v[212:213], v[86:89] offset:512
	flat_store_dwordx4 v[212:213], v[82:85] offset:528
	v_or_b32_e32 v102, 0x100, v102
	v_cvt_pk_bf16_f32 v86, v86, v87
	v_cvt_pk_bf16_f32 v87, v88, v89
	v_cvt_pk_bf16_f32 v88, v82, v83
	v_cvt_pk_bf16_f32 v89, v84, v85
	s_waitcnt lgkmcnt(0)
	v_add_f32_e32 v82, v90, v91
	ds_bpermute_b32 v83, v147, v82
	v_lshl_add_u64 v[84:85], s[6:7], 0, v[102:103]
	s_mov_b64 exec, s[100:101]
	flat_store_dwordx4 v[84:85], v[86:89]
	s_mov_b64 exec, -1
	s_and_saveexec_b64 s[50:51], s[38:39]
	s_cbranch_execz .LBB0_1858
	v_lshl_add_u64 v[84:85], v[210:211], 2, s[44:45]
	s_waitcnt lgkmcnt(0)
	v_add_f32_e32 v82, v82, v83
	flat_atomic_add_f32 v[84:85], v82
.LBB0_1858:
	s_or_b64 exec, exec, s[50:51]
	s_waitcnt lgkmcnt(0)
	v_lshlrev_b64 v[82:83], 11, v[206:207]
	v_pk_add_f32 v[80:81], v[80:81], v[144:145]
	v_pk_add_f32 v[78:79], v[78:79], v[142:143]
	v_lshl_add_u64 v[86:87], v[82:83], 0, v[200:201]
	v_pk_add_f32 v[76:77], v[76:77], v[140:141]
	v_pk_add_f32 v[74:75], v[74:75], v[138:139]
	flat_store_dwordx4 v[208:209], v[78:81]
	flat_store_dwordx4 v[208:209], v[74:77] offset:16
	v_cvt_pk_bf16_f32 v82, v78, v79
	v_cvt_pk_bf16_f32 v83, v80, v81
	v_cvt_pk_bf16_f32 v84, v74, v75
	v_pk_add_f32 v[72:73], v[72:73], v[120:121]
	v_mul_f32_e32 v79, v79, v79
	v_fmac_f32_e32 v79, v78, v78
	v_mul_f32_e32 v78, v81, v81
	v_fmac_f32_e32 v78, v80, v80
	v_mul_f32_e32 v75, v75, v75
	v_add_f32_e32 v78, v79, v78
	v_fmac_f32_e32 v75, v74, v74
	v_add_f32_e32 v74, v78, v75
	v_mul_f32_e32 v75, v77, v77
	v_fmac_f32_e32 v75, v76, v76
	v_pk_add_f32 v[70:71], v[70:71], v[118:119]
	v_cvt_pk_bf16_f32 v85, v76, v77
	v_add_f32_e32 v74, v75, v74
	v_mul_f32_e32 v75, v71, v71
	v_mul_f32_e32 v76, v73, v73
	v_pk_add_f32 v[66:67], v[66:67], v[114:115]
	v_fmac_f32_e32 v75, v70, v70
	v_fmac_f32_e32 v76, v72, v72
	v_add_f32_e32 v75, v75, v76
	v_mul_f32_e32 v76, v67, v67
	v_pk_add_f32 v[68:69], v[68:69], v[116:117]
	v_fmac_f32_e32 v76, v66, v66
	v_add_f32_e32 v75, v75, v76
	v_mul_f32_e32 v76, v69, v69
	v_fmac_f32_e32 v76, v68, v68
	v_add_f32_e32 v75, v76, v75
	v_add_f32_e32 v74, v74, v75
	ds_bpermute_b32 v75, v146, v74
	v_lshlrev_b64 v[86:87], 1, v[86:87]
	v_lshl_add_u64 v[88:89], s[6:7], 0, v[86:87]
	s_mov_b64 exec, s[100:101]
	flat_store_dwordx4 v[88:89], v[82:85]
	s_mov_b64 exec, -1
	flat_store_dwordx4 v[208:209], v[70:73] offset:512
	flat_store_dwordx4 v[208:209], v[66:69] offset:528
	v_or_b32_e32 v86, 0x100, v86
	v_cvt_pk_bf16_f32 v70, v70, v71
	v_cvt_pk_bf16_f32 v71, v72, v73
	v_cvt_pk_bf16_f32 v72, v66, v67
	v_cvt_pk_bf16_f32 v73, v68, v69
	s_waitcnt lgkmcnt(0)
	v_add_f32_e32 v66, v74, v75
	ds_bpermute_b32 v67, v147, v66
	v_lshl_add_u64 v[68:69], s[6:7], 0, v[86:87]
	s_mov_b64 exec, s[100:101]
	flat_store_dwordx4 v[68:69], v[70:73]
	s_mov_b64 exec, -1
	s_and_saveexec_b64 s[50:51], s[38:39]
	s_cbranch_execz .LBB0_1860
	v_lshl_add_u64 v[68:69], v[206:207], 2, s[44:45]
	s_waitcnt lgkmcnt(0)
	v_add_f32_e32 v66, v66, v67
	flat_atomic_add_f32 v[68:69], v66
.LBB0_1860:
	s_or_b64 exec, exec, s[50:51]
	v_add_u32_e32 v134, 0x80, v204
	v_ashrrev_i32_e32 v135, 31, v134
	s_waitcnt lgkmcnt(0)
	v_lshlrev_b64 v[66:67], 13, v[134:135]
	v_lshl_add_u64 v[136:137], v[202:203], 0, v[66:67]
	flat_load_dwordx4 v[138:141], v[136:137]
	flat_load_dwordx4 v[142:145], v[136:137] offset:16
	flat_load_dwordx4 v[118:121], v[136:137] offset:512
	flat_load_dwordx4 v[114:117], v[136:137] offset:528
	v_add_u32_e32 v130, 0x90, v204
	v_ashrrev_i32_e32 v131, 31, v130
	v_add_u32_e32 v126, 0xa0, v204
	v_lshlrev_b64 v[66:67], 13, v[130:131]
	v_ashrrev_i32_e32 v127, 31, v126
	v_add_u32_e32 v122, 0xb0, v204
	v_lshl_add_u64 v[132:133], v[202:203], 0, v[66:67]
	v_lshlrev_b64 v[66:67], 13, v[126:127]
	v_ashrrev_i32_e32 v123, 31, v122
	v_lshl_add_u64 v[128:129], v[202:203], 0, v[66:67]
	v_lshlrev_b64 v[66:67], 13, v[122:123]
	v_lshl_add_u64 v[124:125], v[202:203], 0, v[66:67]
	flat_load_dwordx4 v[110:113], v[132:133]
	flat_load_dwordx4 v[106:109], v[132:133] offset:16
	flat_load_dwordx4 v[102:105], v[132:133] offset:512
	flat_load_dwordx4 v[98:101], v[132:133] offset:528
	flat_load_dwordx4 v[94:97], v[128:129]
	flat_load_dwordx4 v[90:93], v[128:129] offset:16
	flat_load_dwordx4 v[78:81], v[128:129] offset:512
	flat_load_dwordx4 v[74:77], v[128:129] offset:528
	flat_load_dwordx4 v[86:89], v[124:125]
	flat_load_dwordx4 v[82:85], v[124:125] offset:16
	flat_load_dwordx4 v[70:73], v[124:125] offset:512
	flat_load_dwordx4 v[66:69], v[124:125] offset:528
	v_lshlrev_b64 v[148:149], 11, v[134:135]
	v_lshl_add_u64 v[148:149], v[148:149], 0, v[200:201]
	s_waitcnt vmcnt(0) lgkmcnt(0)
	v_pk_add_f32 v[64:65], v[64:65], v[140:141]
	v_pk_add_f32 v[62:63], v[62:63], v[138:139]
	v_pk_add_f32 v[60:61], v[60:61], v[144:145]
	v_pk_add_f32 v[58:59], v[58:59], v[142:143]
	flat_store_dwordx4 v[136:137], v[62:65]
	flat_store_dwordx4 v[136:137], v[58:61] offset:16
	v_cvt_pk_bf16_f32 v138, v62, v63
	v_cvt_pk_bf16_f32 v139, v64, v65
	v_cvt_pk_bf16_f32 v140, v58, v59
	v_lshlrev_b64 v[142:143], 1, v[148:149]
	v_mul_f32_e32 v63, v63, v63
	v_fmac_f32_e32 v63, v62, v62
	v_mul_f32_e32 v62, v65, v65
	v_fmac_f32_e32 v62, v64, v64
	v_mul_f32_e32 v59, v59, v59
	v_add_f32_e32 v62, v63, v62
	v_fmac_f32_e32 v59, v58, v58
	v_add_f32_e32 v58, v62, v59
	v_mul_f32_e32 v59, v61, v61
	v_lshl_add_u64 v[144:145], s[6:7], 0, v[142:143]
	v_fmac_f32_e32 v59, v60, v60
	v_pk_add_f32 v[56:57], v[56:57], v[120:121]
	v_pk_add_f32 v[54:55], v[54:55], v[118:119]
	v_cvt_pk_bf16_f32 v141, v60, v61
	s_mov_b64 exec, s[100:101]
	flat_store_dwordx4 v[144:145], v[138:141]
	s_mov_b64 exec, -1
	v_add_f32_e32 v64, v59, v58
	v_pk_add_f32 v[52:53], v[52:53], v[116:117]
	v_pk_add_f32 v[50:51], v[50:51], v[114:115]
	flat_store_dwordx4 v[136:137], v[54:57] offset:512
	flat_store_dwordx4 v[136:137], v[50:53] offset:528
	v_cvt_pk_bf16_f32 v58, v54, v55
	v_cvt_pk_bf16_f32 v59, v56, v57
	v_cvt_pk_bf16_f32 v60, v50, v51
	v_or_b32_e32 v142, 0x100, v142
	v_mul_f32_e32 v55, v55, v55
	v_fmac_f32_e32 v55, v54, v54
	v_mul_f32_e32 v54, v57, v57
	v_fmac_f32_e32 v54, v56, v56
	v_mul_f32_e32 v51, v51, v51
	v_add_f32_e32 v54, v55, v54
	v_fmac_f32_e32 v51, v50, v50
	v_add_f32_e32 v50, v54, v51
	v_mul_f32_e32 v51, v53, v53
	v_fmac_f32_e32 v51, v52, v52
	v_add_f32_e32 v50, v51, v50
	v_add_f32_e32 v50, v64, v50
	ds_bpermute_b32 v51, v146, v50
	v_lshl_add_u64 v[62:63], s[6:7], 0, v[142:143]
	v_cvt_pk_bf16_f32 v61, v52, v53
	s_mov_b64 exec, s[100:101]
	flat_store_dwordx4 v[62:63], v[58:61]
	s_mov_b64 exec, -1
	s_waitcnt lgkmcnt(0)
	v_add_f32_e32 v50, v50, v51
	ds_bpermute_b32 v51, v147, v50
	s_and_saveexec_b64 s[50:51], s[38:39]
	s_cbranch_execz .LBB0_1862
	v_lshl_add_u64 v[52:53], v[134:135], 2, s[44:45]
	s_waitcnt lgkmcnt(0)
	v_add_f32_e32 v50, v50, v51
	flat_atomic_add_f32 v[52:53], v50
.LBB0_1862:
	s_or_b64 exec, exec, s[50:51]
	s_waitcnt lgkmcnt(0)
	v_lshlrev_b64 v[50:51], 11, v[130:131]
	v_pk_add_f32 v[48:49], v[48:49], v[112:113]
	v_pk_add_f32 v[46:47], v[46:47], v[110:111]
	v_lshl_add_u64 v[54:55], v[50:51], 0, v[200:201]
	v_pk_add_f32 v[44:45], v[44:45], v[108:109]
	v_pk_add_f32 v[42:43], v[42:43], v[106:107]
	flat_store_dwordx4 v[132:133], v[46:49]
	flat_store_dwordx4 v[132:133], v[42:45] offset:16
	v_cvt_pk_bf16_f32 v50, v46, v47
	v_cvt_pk_bf16_f32 v51, v48, v49
	v_cvt_pk_bf16_f32 v52, v42, v43
	v_pk_add_f32 v[40:41], v[40:41], v[104:105]
	v_mul_f32_e32 v47, v47, v47
	v_fmac_f32_e32 v47, v46, v46
	v_mul_f32_e32 v46, v49, v49
	v_fmac_f32_e32 v46, v48, v48
	v_mul_f32_e32 v43, v43, v43
	v_add_f32_e32 v46, v47, v46
	v_fmac_f32_e32 v43, v42, v42
	v_add_f32_e32 v42, v46, v43
	v_mul_f32_e32 v43, v45, v45
	v_fmac_f32_e32 v43, v44, v44
	v_pk_add_f32 v[38:39], v[38:39], v[102:103]
	v_cvt_pk_bf16_f32 v53, v44, v45
	v_add_f32_e32 v42, v43, v42
	v_mul_f32_e32 v43, v39, v39
	v_mul_f32_e32 v44, v41, v41
	v_pk_add_f32 v[34:35], v[34:35], v[98:99]
	v_fmac_f32_e32 v43, v38, v38
	v_fmac_f32_e32 v44, v40, v40
	v_add_f32_e32 v43, v43, v44
	v_mul_f32_e32 v44, v35, v35
	v_pk_add_f32 v[36:37], v[36:37], v[100:101]
	v_fmac_f32_e32 v44, v34, v34
	v_add_f32_e32 v43, v43, v44
	v_mul_f32_e32 v44, v37, v37
	v_fmac_f32_e32 v44, v36, v36
	v_add_f32_e32 v43, v44, v43
	v_add_f32_e32 v42, v42, v43
	ds_bpermute_b32 v43, v146, v42
	v_lshlrev_b64 v[54:55], 1, v[54:55]
	v_lshl_add_u64 v[56:57], s[6:7], 0, v[54:55]
	s_mov_b64 exec, s[100:101]
	flat_store_dwordx4 v[56:57], v[50:53]
	s_mov_b64 exec, -1
	flat_store_dwordx4 v[132:133], v[38:41] offset:512
	flat_store_dwordx4 v[132:133], v[34:37] offset:528
	v_or_b32_e32 v54, 0x100, v54
	v_cvt_pk_bf16_f32 v38, v38, v39
	v_cvt_pk_bf16_f32 v39, v40, v41
	v_cvt_pk_bf16_f32 v40, v34, v35
	v_cvt_pk_bf16_f32 v41, v36, v37
	s_waitcnt lgkmcnt(0)
	v_add_f32_e32 v34, v42, v43
	ds_bpermute_b32 v35, v147, v34
	v_lshl_add_u64 v[36:37], s[6:7], 0, v[54:55]
	s_mov_b64 exec, s[100:101]
	flat_store_dwordx4 v[36:37], v[38:41]
	s_mov_b64 exec, -1
	s_and_saveexec_b64 s[50:51], s[38:39]
	s_cbranch_execz .LBB0_1864
	v_lshl_add_u64 v[36:37], v[130:131], 2, s[44:45]
	s_waitcnt lgkmcnt(0)
	v_add_f32_e32 v34, v34, v35
	flat_atomic_add_f32 v[36:37], v34
.LBB0_1864:
	s_or_b64 exec, exec, s[50:51]
	s_waitcnt lgkmcnt(0)
	v_lshlrev_b64 v[34:35], 11, v[126:127]
	v_pk_add_f32 v[32:33], v[32:33], v[96:97]
	v_pk_add_f32 v[30:31], v[30:31], v[94:95]
	v_lshl_add_u64 v[38:39], v[34:35], 0, v[200:201]
	v_pk_add_f32 v[28:29], v[28:29], v[92:93]
	v_pk_add_f32 v[26:27], v[26:27], v[90:91]
	flat_store_dwordx4 v[128:129], v[30:33]
	flat_store_dwordx4 v[128:129], v[26:29] offset:16
	v_cvt_pk_bf16_f32 v34, v30, v31
	v_cvt_pk_bf16_f32 v35, v32, v33
	v_cvt_pk_bf16_f32 v36, v26, v27
	v_pk_add_f32 v[24:25], v[24:25], v[80:81]
	v_mul_f32_e32 v31, v31, v31
	v_fmac_f32_e32 v31, v30, v30
	v_mul_f32_e32 v30, v33, v33
	v_fmac_f32_e32 v30, v32, v32
	v_mul_f32_e32 v27, v27, v27
	v_add_f32_e32 v30, v31, v30
	v_fmac_f32_e32 v27, v26, v26
	v_add_f32_e32 v26, v30, v27
	v_mul_f32_e32 v27, v29, v29
	v_fmac_f32_e32 v27, v28, v28
	v_pk_add_f32 v[22:23], v[22:23], v[78:79]
	v_cvt_pk_bf16_f32 v37, v28, v29
	v_add_f32_e32 v26, v27, v26
	v_mul_f32_e32 v27, v23, v23
	v_mul_f32_e32 v28, v25, v25
	v_pk_add_f32 v[18:19], v[18:19], v[74:75]
	v_fmac_f32_e32 v27, v22, v22
	v_fmac_f32_e32 v28, v24, v24
	v_add_f32_e32 v27, v27, v28
	v_mul_f32_e32 v28, v19, v19
	v_pk_add_f32 v[20:21], v[20:21], v[76:77]
	v_fmac_f32_e32 v28, v18, v18
	v_add_f32_e32 v27, v27, v28
	v_mul_f32_e32 v28, v21, v21
	v_fmac_f32_e32 v28, v20, v20
	v_add_f32_e32 v27, v28, v27
	v_add_f32_e32 v26, v26, v27
	ds_bpermute_b32 v27, v146, v26
	v_lshlrev_b64 v[38:39], 1, v[38:39]
	v_lshl_add_u64 v[40:41], s[6:7], 0, v[38:39]
	s_mov_b64 exec, s[100:101]
	flat_store_dwordx4 v[40:41], v[34:37]
	s_mov_b64 exec, -1
	flat_store_dwordx4 v[128:129], v[22:25] offset:512
	flat_store_dwordx4 v[128:129], v[18:21] offset:528
	v_or_b32_e32 v38, 0x100, v38
	v_cvt_pk_bf16_f32 v22, v22, v23
	v_cvt_pk_bf16_f32 v23, v24, v25
	v_cvt_pk_bf16_f32 v24, v18, v19
	v_cvt_pk_bf16_f32 v25, v20, v21
	s_waitcnt lgkmcnt(0)
	v_add_f32_e32 v18, v26, v27
	ds_bpermute_b32 v19, v147, v18
	v_lshl_add_u64 v[20:21], s[6:7], 0, v[38:39]
	s_mov_b64 exec, s[100:101]
	flat_store_dwordx4 v[20:21], v[22:25]
	s_mov_b64 exec, -1
	s_and_saveexec_b64 s[50:51], s[38:39]
	s_cbranch_execz .LBB0_1866
	v_lshl_add_u64 v[20:21], v[126:127], 2, s[44:45]
	s_waitcnt lgkmcnt(0)
	v_add_f32_e32 v18, v18, v19
	flat_atomic_add_f32 v[20:21], v18
.LBB0_1866:
	s_or_b64 exec, exec, s[50:51]
	s_waitcnt lgkmcnt(0)
	v_lshlrev_b64 v[18:19], 11, v[122:123]
	v_pk_add_f32 v[16:17], v[16:17], v[88:89]
	v_pk_add_f32 v[14:15], v[14:15], v[86:87]
	v_lshl_add_u64 v[22:23], v[18:19], 0, v[200:201]
	v_pk_add_f32 v[12:13], v[12:13], v[84:85]
	v_pk_add_f32 v[10:11], v[10:11], v[82:83]
	flat_store_dwordx4 v[124:125], v[14:17]
	flat_store_dwordx4 v[124:125], v[10:13] offset:16
	v_cvt_pk_bf16_f32 v18, v14, v15
	v_cvt_pk_bf16_f32 v19, v16, v17
	v_cvt_pk_bf16_f32 v20, v10, v11
	v_pk_add_f32 v[8:9], v[8:9], v[72:73]
	v_mul_f32_e32 v15, v15, v15
	v_fmac_f32_e32 v15, v14, v14
	v_mul_f32_e32 v14, v17, v17
	v_fmac_f32_e32 v14, v16, v16
	v_mul_f32_e32 v11, v11, v11
	v_add_f32_e32 v14, v15, v14
	v_fmac_f32_e32 v11, v10, v10
	v_add_f32_e32 v10, v14, v11
	v_mul_f32_e32 v11, v13, v13
	v_fmac_f32_e32 v11, v12, v12
	v_pk_add_f32 v[6:7], v[6:7], v[70:71]
	v_cvt_pk_bf16_f32 v21, v12, v13
	v_add_f32_e32 v10, v11, v10
	v_mul_f32_e32 v11, v7, v7
	v_mul_f32_e32 v12, v9, v9
	v_pk_add_f32 v[2:3], v[2:3], v[66:67]
	v_fmac_f32_e32 v11, v6, v6
	v_fmac_f32_e32 v12, v8, v8
	v_add_f32_e32 v11, v11, v12
	v_mul_f32_e32 v12, v3, v3
	v_pk_add_f32 v[4:5], v[4:5], v[68:69]
	v_fmac_f32_e32 v12, v2, v2
	v_add_f32_e32 v11, v11, v12
	v_mul_f32_e32 v12, v5, v5
	v_fmac_f32_e32 v12, v4, v4
	v_add_f32_e32 v11, v12, v11
	v_add_f32_e32 v10, v10, v11
	ds_bpermute_b32 v11, v146, v10
	v_lshlrev_b64 v[22:23], 1, v[22:23]
	v_lshl_add_u64 v[24:25], s[6:7], 0, v[22:23]
	s_mov_b64 exec, s[100:101]
	flat_store_dwordx4 v[24:25], v[18:21]
	s_mov_b64 exec, -1
	flat_store_dwordx4 v[124:125], v[6:9] offset:512
	flat_store_dwordx4 v[124:125], v[2:5] offset:528
	v_or_b32_e32 v22, 0x100, v22
	v_cvt_pk_bf16_f32 v6, v6, v7
	v_cvt_pk_bf16_f32 v7, v8, v9
	v_cvt_pk_bf16_f32 v8, v2, v3
	v_cvt_pk_bf16_f32 v9, v4, v5
	s_waitcnt lgkmcnt(0)
	v_add_f32_e32 v2, v10, v11
	ds_bpermute_b32 v3, v147, v2
	v_lshl_add_u64 v[4:5], s[6:7], 0, v[22:23]
	s_mov_b64 exec, s[100:101]
	flat_store_dwordx4 v[4:5], v[6:9]
	s_mov_b64 exec, -1
	s_and_saveexec_b64 s[50:51], s[38:39]
	s_cbranch_execz .LBB0_1868
	v_lshl_add_u64 v[4:5], v[122:123], 2, s[44:45]
	s_waitcnt lgkmcnt(0)
	v_add_f32_e32 v2, v2, v3
	flat_atomic_add_f32 v[4:5], v2

.LBB0_1923:
	v_readlane_b32 s1, v252, 32
	v_readfirstlane_b32 s0, v222
	s_ashr_i32 s0, s0, 6
	v_readlane_b32 s4, v255, 0
	s_add_i32 s0, s0, s1
	v_readlane_b32 s5, v255, 1
	v_readlane_b32 s6, v255, 2
	v_readlane_b32 s7, v255, 3
	v_readlane_b32 s8, v255, 4
	v_readlane_b32 s9, v255, 5
	s_cmpk_gt_i32 s0, 0x1fff
	v_readlane_b32 s12, v252, 33
	v_readlane_b32 s10, v255, 6
	v_readlane_b32 s11, v255, 7
	v_readlane_b32 s13, v252, 34
	s_cbranch_scc1 .LBB0_1926
	v_and_b32_e32 v0, 63, v222
	v_lshlrev_b32_e32 v10, 4, v0
	v_mov_b32_e32 v11, 0
	v_lshl_add_u64 v[0:1], s[4:5], 0, v[10:11]
	s_mov_b64 s[4:5], 0x1400
	v_lshl_add_u64 v[4:5], v[0:1], 0, s[4:5]
	s_mov_b64 s[4:5], 0x1800
	v_lshl_add_u64 v[6:7], v[0:1], 0, s[4:5]
	s_mov_b64 s[4:5], 0x1c00
	s_ashr_i32 s1, s0, 31
	v_lshl_add_u64 v[8:9], v[0:1], 0, s[4:5]
	s_lshl_b64 s[4:5], s[0:1], 13
	s_add_u32 s4, s6, s4
	s_addc_u32 s5, s7, s5
	s_mov_b64 s[2:3], 0x1000
	v_lshl_add_u64 v[10:11], s[4:5], 0, v[10:11]
	s_ashr_i32 s13, s12, 31
	v_lshl_add_u64 v[2:3], v[0:1], 0, s[2:3]
	v_lshl_add_u64 v[10:11], v[10:11], 0, s[2:3]
	s_lshl_b64 s[2:3], s[12:13], 13
	s_lshl_b64 s[4:5], s[0:1], 2
	s_add_u32 s1, s8, s4
	s_addc_u32 s5, s9, s5
	s_add_u32 s4, s1, 0x20000
	s_addc_u32 s5, s5, 0
	s_lshl_b64 s[6:7], s[12:13], 2
	v_mov_b32_e32 v12, 0x358637bd
	s_mov_b32 s1, 0x800000
	s_movk_i32 s8, 0xf400
	s_movk_i32 s9, 0xf800
	s_movk_i32 s10, 0xfc00
	global_load_dwordx4 v[32:35], v[0:1], off
	global_load_dwordx4 v[36:39], v[0:1], off offset:1024
	global_load_dwordx4 v[40:43], v[0:1], off offset:2048
	global_load_dwordx4 v[44:47], v[0:1], off offset:3072
	global_load_dwordx4 v[48:51], v[2:3], off
	global_load_dwordx4 v[52:55], v[4:5], off
	global_load_dwordx4 v[56:59], v[6:7], off
	global_load_dwordx4 v[60:63], v[8:9], off
	v_mov_b32_e32 v129, 0
	global_load_dword v13, v129, s[4:5]
	global_load_dwordx4 v[64:67], v[10:11], off offset:-4096
	global_load_dwordx4 v[68:71], v[10:11], off offset:-3072
	global_load_dwordx4 v[72:75], v[10:11], off offset:-2048
	global_load_dwordx4 v[76:79], v[10:11], off offset:-1024
	global_load_dwordx4 v[80:83], v[10:11], off
	global_load_dwordx4 v[84:87], v[10:11], off offset:1024
	global_load_dwordx4 v[88:91], v[10:11], off offset:2048
	global_load_dwordx4 v[92:95], v[10:11], off offset:3072
	s_waitcnt vmcnt(0)
.LBB0_1925:
	s_add_i32 s0, s0, s12
	s_add_u32 s4, s4, s6
	s_addc_u32 s5, s5, s7
	v_lshl_add_u64 v[26:27], v[10:11], 0, s[2:3]
	s_cmpk_gt_i32 s0, 0x1fff
	s_cbranch_scc1 .Lfin_proc
	global_load_dword v128, v129, s[4:5]
	global_load_dwordx4 v[96:99], v[26:27], off offset:-4096
	global_load_dwordx4 v[100:103], v[26:27], off offset:-3072
	global_load_dwordx4 v[104:107], v[26:27], off offset:-2048
	global_load_dwordx4 v[108:111], v[26:27], off offset:-1024
	global_load_dwordx4 v[112:115], v[26:27], off
	global_load_dwordx4 v[116:119], v[26:27], off offset:1024
	global_load_dwordx4 v[120:123], v[26:27], off offset:2048
	global_load_dwordx4 v[124:127], v[26:27], off offset:3072
.Lfin_proc:
	v_fmamk_f32 v13, v13, 0x3a000000, v12
	v_mul_f32_e32 v30, 0x4b800000, v13
	v_cmp_gt_f32_e32 vcc, s1, v13
	s_nop 1
	v_cndmask_b32_e32 v13, v13, v30, vcc
	v_rsq_f32_e32 v13, v13
	s_nop 0
	v_mul_f32_e32 v30, 0x45800000, v13
	v_cndmask_b32_e32 v30, v13, v30, vcc
	v_pk_mul_f32 v[64:65], v[30:31], v[64:65] op_sel_hi:[0,1]
	v_pk_mul_f32 v[66:67], v[30:31], v[66:67] op_sel_hi:[0,1]
	v_pk_mul_f32 v[64:65], v[64:65], v[32:33]
	v_pk_mul_f32 v[66:67], v[66:67], v[34:35]
	global_store_dwordx4 v[10:11], v[64:67], off offset:-4096
	v_pk_mul_f32 v[68:69], v[30:31], v[68:69] op_sel_hi:[0,1]
	v_pk_mul_f32 v[70:71], v[30:31], v[70:71] op_sel_hi:[0,1]
	v_pk_mul_f32 v[68:69], v[68:69], v[36:37]
	v_pk_mul_f32 v[70:71], v[70:71], v[38:39]
	global_store_dwordx4 v[10:11], v[68:71], off offset:-3072
	v_pk_mul_f32 v[72:73], v[30:31], v[72:73] op_sel_hi:[0,1]
	v_pk_mul_f32 v[74:75], v[30:31], v[74:75] op_sel_hi:[0,1]
	v_pk_mul_f32 v[72:73], v[72:73], v[40:41]
	v_pk_mul_f32 v[74:75], v[74:75], v[42:43]
	global_store_dwordx4 v[10:11], v[72:75], off offset:-2048
	v_pk_mul_f32 v[76:77], v[30:31], v[76:77] op_sel_hi:[0,1]
	v_pk_mul_f32 v[78:79], v[30:31], v[78:79] op_sel_hi:[0,1]
	v_pk_mul_f32 v[76:77], v[76:77], v[44:45]
	v_pk_mul_f32 v[78:79], v[78:79], v[46:47]
	global_store_dwordx4 v[10:11], v[76:79], off offset:-1024
	v_pk_mul_f32 v[80:81], v[30:31], v[80:81] op_sel_hi:[0,1]
	v_pk_mul_f32 v[82:83], v[30:31], v[82:83] op_sel_hi:[0,1]
	v_pk_mul_f32 v[80:81], v[80:81], v[48:49]
	v_pk_mul_f32 v[82:83], v[82:83], v[50:51]
	global_store_dwordx4 v[10:11], v[80:83], off
	v_pk_mul_f32 v[84:85], v[30:31], v[84:85] op_sel_hi:[0,1]
	v_pk_mul_f32 v[86:87], v[30:31], v[86:87] op_sel_hi:[0,1]
	v_pk_mul_f32 v[84:85], v[84:85], v[52:53]
	v_pk_mul_f32 v[86:87], v[86:87], v[54:55]
	global_store_dwordx4 v[10:11], v[84:87], off offset:1024
	v_pk_mul_f32 v[88:89], v[30:31], v[88:89] op_sel_hi:[0,1]
	v_pk_mul_f32 v[90:91], v[30:31], v[90:91] op_sel_hi:[0,1]
	v_pk_mul_f32 v[88:89], v[88:89], v[56:57]
	v_pk_mul_f32 v[90:91], v[90:91], v[58:59]
	global_store_dwordx4 v[10:11], v[88:91], off offset:2048
	v_pk_mul_f32 v[92:93], v[30:31], v[92:93] op_sel_hi:[0,1]
	v_pk_mul_f32 v[94:95], v[30:31], v[94:95] op_sel_hi:[0,1]
	v_pk_mul_f32 v[92:93], v[92:93], v[60:61]
	v_pk_mul_f32 v[94:95], v[94:95], v[62:63]
	global_store_dwordx4 v[10:11], v[92:95], off offset:3072
	s_cbranch_scc1 .LBB0_1926
	s_waitcnt vmcnt(8)
	v_mov_b32_e32 v13, v128
	v_mov_b64_e32 v[64:65], v[96:97]
	v_mov_b64_e32 v[66:67], v[98:99]
	v_mov_b64_e32 v[68:69], v[100:101]
	v_mov_b64_e32 v[70:71], v[102:103]
	v_mov_b64_e32 v[72:73], v[104:105]
	v_mov_b64_e32 v[74:75], v[106:107]
	v_mov_b64_e32 v[76:77], v[108:109]
	v_mov_b64_e32 v[78:79], v[110:111]
	v_mov_b64_e32 v[80:81], v[112:113]
	v_mov_b64_e32 v[82:83], v[114:115]
	v_mov_b64_e32 v[84:85], v[116:117]
	v_mov_b64_e32 v[86:87], v[118:119]
	v_mov_b64_e32 v[88:89], v[120:121]
	v_mov_b64_e32 v[90:91], v[122:123]
	v_mov_b64_e32 v[92:93], v[124:125]
	v_mov_b64_e32 v[94:95], v[126:127]
	v_mov_b64_e32 v[10:11], v[26:27]
	s_branch .LBB0_1925
